# F1 K-loop: first two vmcnt waits of a unit's first iteration relaxed to vmcnt(22) for units after the first (do not wait on the previous epilogue's stores)
# speedup vs baseline: 1.0909x; 1.0002x over previous
; #define PG8_STAGE(bufoff, gbase, voff) do { _Pragma("unroll") for (int _i = 0; _i < 2; ++_i) \
;         __builtin_amdgcn_global_load_lds((const unsigned*)((const char*)(gbase) + (voff)[_i]), (PG8_LAS unsigned*)(lds + (bufoff) + ldsw + _i * 8192), 16, 0, 0); } while (0)
; #define PG8_LDA(dst, b, h) do { _Pragma("unroll") for (int m = 0; m < 4; ++m) _Pragma("unroll") for (int k = 0; k < 2; ++k) dst[m][k] = *(const PG8_LAS bf16x8*)(lds + PG8_SA(b, h) + aoff + m * 2048 + k * 1024); } while (0)
; #define PG8_LDB(dst, b, h) do { _Pragma("unroll") for (int n = 0; n < 2; ++n) _Pragma("unroll") for (int k = 0; k < 2; ++k) dst[n][k] = *(const PG8_LAS bf16x8*)(lds + PG8_SB(b, h) + boff + n * 2048 + k * 1024); } while (0)
; #define PG8_WAIT_L(n) asm volatile("s_waitcnt lgkmcnt(" #n ")" ::: "memory")
; #define PG8_BAR __builtin_amdgcn_s_barrier()
; #define PG8_SCHED __builtin_amdgcn_sched_barrier(0)
;     ...
;         const char* nA = has_next ? (const char*)g.A + (size_t)nxt.pm * tstep : cA; const char* nB = has_next ? (const char*)g.Bt + (size_t)nxt.pn * tstep : cB;
;         for (int t = 0; t < nt * KREP; t += 2) {
;             const bool last = (t == nt * KREP - 2);
;             const int t1w = KREP > 1 ? ((t + 1) & (nt - 1)) : t + 1, t2w = KREP > 1 ? ((t + 2) & (nt - 1)) : t + 2;
;             const char* a1 = cA + (size_t)t1w * kstep;
;             const char* a2 = last ? nA : cA + (size_t)t2w * kstep; const char* b2 = last ? nB : cB + (size_t)t2w * kstep;
;             const char* a3 = a2 + kstep; const char* b3 = b2 + kstep;
;             if (last && has_next) S.a_ready(nxt);
;             const int relax = __builtin_amdgcn_readfirstlane((MK_RELAXW && t == 0 && ui > 0) ? 1 : 0);
;             if constexpr (SP2) {
;             PG8_LDB(B0, 0, 0); PG8_LDB(B1, 0, 1); PG8_SCHED; PG8_LDA(At, 0, 0); PG8_STAGE(PG8_SA(1, 1), a1 + hstep, voffA);
;             PG8_WAIT_V_SEL(relax);
;             PG8_WAIT_L(0); PG8_BAR; PG8_MMA(0, 0, At, B0); PG8_MMA(0, 1, At, B1); PG8_BAR; PG8_SCHED;
;     ...
; #pragma unroll
;         for (int a = 0; a < 2; ++a)
; #pragma unroll
;             for (int b = 0; b < 2; ++b)
; #pragma unroll
;                 for (int m = 0; m < 4; ++m)
; #pragma unroll
;                     for (int n = 0; n < 2; ++n) acc[a][b][m][n] = (f32x4){0.f, 0.f, 0.f, 0.f};
;         cur = nxt; cA = nA; cB = nB; ++ui;
.LBB0_1326:
	s_ashr_i32 s89, s88, 31
	s_lshl_b64 s[40:41], s[88:89], 20
	s_add_u32 s90, s23, s40
	s_addc_u32 s91, s31, s41
	s_and_b64 s[40:41], s[8:9], exec
	s_cselect_b32 s59, s91, s13
	s_cselect_b32 s64, s90, s12
	s_ashr_i32 s87, s86, 31
	s_lshl_b64 s[40:41], s[86:87], 20
	s_add_u32 s92, s56, s40
	s_addc_u32 s93, s57, s41
	s_and_b64 s[40:41], s[8:9], exec
	s_cselect_b32 s65, s93, s97
	s_cselect_b32 s87, s92, s96
	s_add_u32 s66, s96, 0x100
	v_mov_b64_e32 v[2:3], 0
	v_mov_b64_e32 v[4:5], 0
	v_mov_b64_e32 v[6:7], 0
	v_mov_b64_e32 v[8:9], 0
	v_mov_b64_e32 v[10:11], 0
	v_mov_b64_e32 v[12:13], 0
	v_mov_b64_e32 v[14:15], 0
	v_mov_b64_e32 v[16:17], 0
	v_mov_b64_e32 v[18:19], 0
	v_mov_b64_e32 v[20:21], 0
	v_mov_b64_e32 v[22:23], 0
	v_mov_b64_e32 v[24:25], 0
	v_mov_b64_e32 v[26:27], 0
	v_mov_b64_e32 v[28:29], 0
	v_mov_b64_e32 v[30:31], 0
	v_mov_b64_e32 v[32:33], 0
	v_mov_b64_e32 v[34:35], 0
	v_mov_b64_e32 v[36:37], 0
	v_mov_b64_e32 v[38:39], 0
	v_mov_b64_e32 v[40:41], 0
	v_mov_b64_e32 v[42:43], 0
	v_mov_b64_e32 v[44:45], 0
	v_mov_b64_e32 v[46:47], 0
	v_mov_b64_e32 v[48:49], 0
	v_mov_b64_e32 v[50:51], 0
	v_mov_b64_e32 v[52:53], 0
	v_mov_b64_e32 v[54:55], 0
	v_mov_b64_e32 v[56:57], 0
	v_mov_b64_e32 v[58:59], 0
	v_mov_b64_e32 v[60:61], 0
	v_mov_b64_e32 v[62:63], 0
	v_mov_b64_e32 v[64:65], 0
	v_mov_b64_e32 v[74:75], 0
	v_mov_b64_e32 v[76:77], 0
	v_mov_b64_e32 v[78:79], 0
	v_mov_b64_e32 v[80:81], 0
	v_mov_b64_e32 v[86:87], 0
	v_mov_b64_e32 v[88:89], 0
	v_mov_b64_e32 v[90:91], 0
	v_mov_b64_e32 v[92:93], 0
	v_mov_b64_e32 v[94:95], 0
	v_mov_b64_e32 v[96:97], 0
	v_mov_b64_e32 v[98:99], 0
	v_mov_b64_e32 v[100:101], 0
	v_mov_b64_e32 v[102:103], 0
	v_mov_b64_e32 v[104:105], 0
	v_mov_b64_e32 v[106:107], 0
	v_mov_b64_e32 v[108:109], 0
	v_mov_b64_e32 v[110:111], 0
	v_mov_b64_e32 v[112:113], 0
	v_mov_b64_e32 v[114:115], 0
	v_mov_b64_e32 v[116:117], 0
	v_mov_b64_e32 v[118:119], 0
	v_mov_b64_e32 v[120:121], 0
	v_mov_b64_e32 v[122:123], 0
	v_mov_b64_e32 v[124:125], 0
	v_mov_b64_e32 v[126:127], 0
	v_mov_b64_e32 v[128:129], 0
	v_mov_b64_e32 v[130:131], 0
	v_mov_b64_e32 v[132:133], 0
	v_mov_b64_e32 v[134:135], 0
	v_mov_b64_e32 v[136:137], 0
	v_mov_b64_e32 v[138:139], 0
	v_mov_b64_e32 v[140:141], 0
	s_addc_u32 s67, s97, 0
	s_mov_b32 s0, -2
	s_cmp_lg_u32 s11, 0
	s_cselect_b32 s101, 1, 0
	v_add_u32_e32 v200, 0x10000, v203
.LBB0_1327:
	s_add_u32 s96, s12, 0x100
	s_addc_u32 s97, s13, 0
	s_add_i32 s51, 0, 0x10000
	s_cmp_eq_u32 s0, 28
	s_cselect_b32 s41, s59, s97
	s_cselect_b32 s40, s64, s96
	s_cselect_b32 vcc_hi, s65, s67
	s_cselect_b32 vcc_lo, s87, s66
	s_add_i32 s19, 0, 0x14000
	ds_read_b128 v[66:69], v200
	ds_read_b128 v[70:73], v200 offset:1024
	ds_read_b128 v[82:85], v200 offset:2048
	ds_read_b128 v[142:145], v200 offset:3072
	ds_read_b128 v[146:149], v200 offset:16384
	ds_read_b128 v[150:153], v200 offset:17408
	ds_read_b128 v[154:157], v200 offset:18432
	ds_read_b128 v[158:161], v200 offset:19456
	s_add_i32 m0, s95, 0xc000
	ds_read_b128 v[162:165], v219
	ds_read_b128 v[166:169], v219 offset:1024
	ds_read_b128 v[170:173], v219 offset:2048
	ds_read_b128 v[174:177], v219 offset:3072
	ds_read_b128 v[178:181], v219 offset:4096
	ds_read_b128 v[184:187], v219 offset:5120
	ds_read_b128 v[220:223], v219 offset:6144
	ds_read_b128 v[224:227], v219 offset:7168
	global_load_lds_dwordx4 v196, s[12:13]
	s_add_i32 m0, s95, 0xe000
	s_nop 0
	global_load_lds_dwordx4 v198, s[12:13]
	s_cmp_eq_u32 s101, 1
	s_cbranch_scc1 .Lrlx_f1_0
	s_waitcnt vmcnt(8)
.Lrlx_f1_0_b:
	s_waitcnt lgkmcnt(0)
	s_setprio 1
	s_barrier
	v_mfma_f32_16x16x32_bf16 v[114:117], v[66:69], v[162:165], v[114:117]
	v_mfma_f32_16x16x32_bf16 v[114:117], v[70:73], v[166:169], v[114:117]
	v_mfma_f32_16x16x32_bf16 v[110:113], v[66:69], v[170:173], v[110:113]
	v_mfma_f32_16x16x32_bf16 v[110:113], v[70:73], v[174:177], v[110:113]
	v_mfma_f32_16x16x32_bf16 v[78:81], v[66:69], v[178:181], v[78:81]
	v_mfma_f32_16x16x32_bf16 v[78:81], v[70:73], v[184:187], v[78:81]
	v_mfma_f32_16x16x32_bf16 v[74:77], v[66:69], v[220:223], v[74:77]
	v_mfma_f32_16x16x32_bf16 v[74:77], v[70:73], v[224:227], v[74:77]
	v_mfma_f32_16x16x32_bf16 v[134:137], v[82:85], v[220:223], v[134:137]
	v_mfma_f32_16x16x32_bf16 v[134:137], v[142:145], v[224:227], v[134:137]
	v_mfma_f32_16x16x32_bf16 v[138:141], v[82:85], v[178:181], v[138:141]
	v_mfma_f32_16x16x32_bf16 v[138:141], v[142:145], v[184:187], v[138:141]
	v_mfma_f32_16x16x32_bf16 v[102:105], v[82:85], v[170:173], v[102:105]
	v_mfma_f32_16x16x32_bf16 v[102:105], v[142:145], v[174:177], v[102:105]
	v_mfma_f32_16x16x32_bf16 v[106:109], v[82:85], v[162:165], v[106:109]
	v_mfma_f32_16x16x32_bf16 v[106:109], v[142:145], v[166:169], v[106:109]
	v_mfma_f32_16x16x32_bf16 v[98:101], v[146:149], v[162:165], v[98:101]
	v_mfma_f32_16x16x32_bf16 v[98:101], v[150:153], v[166:169], v[98:101]
	v_mfma_f32_16x16x32_bf16 v[94:97], v[146:149], v[170:173], v[94:97]
	v_mfma_f32_16x16x32_bf16 v[94:97], v[150:153], v[174:177], v[94:97]
	v_mfma_f32_16x16x32_bf16 v[130:133], v[146:149], v[178:181], v[130:133]
	v_mfma_f32_16x16x32_bf16 v[130:133], v[150:153], v[184:187], v[130:133]
	v_mfma_f32_16x16x32_bf16 v[126:129], v[146:149], v[220:223], v[126:129]
	v_mfma_f32_16x16x32_bf16 v[126:129], v[150:153], v[224:227], v[126:129]
	v_mfma_f32_16x16x32_bf16 v[118:121], v[154:157], v[220:223], v[118:121]
	v_mfma_f32_16x16x32_bf16 v[118:121], v[158:161], v[224:227], v[118:121]
	v_mfma_f32_16x16x32_bf16 v[122:125], v[154:157], v[178:181], v[122:125]
	v_mfma_f32_16x16x32_bf16 v[122:125], v[158:161], v[184:187], v[122:125]
	v_mfma_f32_16x16x32_bf16 v[86:89], v[154:157], v[170:173], v[86:89]
	v_mfma_f32_16x16x32_bf16 v[86:89], v[158:161], v[174:177], v[86:89]
	v_mfma_f32_16x16x32_bf16 v[90:93], v[154:157], v[162:165], v[90:93]
	v_mfma_f32_16x16x32_bf16 v[90:93], v[158:161], v[166:169], v[90:93]
	s_barrier
	s_setprio 0
	s_add_i32 s12, s51, s37
	s_mov_b32 m0, s12
	ds_read_b128 v[162:165], v219 offset:16384
	ds_read_b128 v[166:169], v219 offset:17408
	ds_read_b128 v[170:173], v219 offset:18432
	ds_read_b128 v[174:177], v219 offset:19456
	ds_read_b128 v[178:181], v219 offset:20480
	ds_read_b128 v[184:187], v219 offset:21504
	ds_read_b128 v[220:223], v219 offset:22528
	ds_read_b128 v[224:227], v219 offset:23552
	global_load_lds_dwordx4 v182, vcc
	s_add_i32 m0, s12, 0x2000
	s_add_u32 s12, vcc_lo, 0x80000
	s_addc_u32 s13, vcc_hi, 0
	s_add_i32 s19, s19, s37
	global_load_lds_dwordx4 v192, vcc
	s_mov_b32 m0, s19
	s_nop 0
	global_load_lds_dwordx4 v182, s[12:13]
	s_add_i32 m0, s19, 0x2000
	s_nop 0
	global_load_lds_dwordx4 v192, s[12:13]
	s_mov_b32 m0, s95
	s_nop 0
	global_load_lds_dwordx4 v188, s[40:41]
	s_mov_b32 m0, s20
	s_nop 0
	global_load_lds_dwordx4 v190, s[40:41]
	s_cmp_eq_u32 s101, 1
	s_cbranch_scc1 .Lrlx_f1_1
	s_waitcnt vmcnt(8)
; #define PG8_STAGE(bufoff, gbase, voff) do { _Pragma("unroll") for (int _i = 0; _i < 2; ++_i) \
;         __builtin_amdgcn_global_load_lds((const unsigned*)((const char*)(gbase) + (voff)[_i]), (PG8_LAS unsigned*)(lds + (bufoff) + ldsw + _i * 8192), 16, 0, 0); } while (0)
; #define PG8_LDA(dst, b, h) do { _Pragma("unroll") for (int m = 0; m < 4; ++m) _Pragma("unroll") for (int k = 0; k < 2; ++k) dst[m][k] = *(const PG8_LAS bf16x8*)(lds + PG8_SA(b, h) + aoff + m * 2048 + k * 1024); } while (0)
; #define PG8_LDB(dst, b, h) do { _Pragma("unroll") for (int n = 0; n < 2; ++n) _Pragma("unroll") for (int k = 0; k < 2; ++k) dst[n][k] = *(const PG8_LAS bf16x8*)(lds + PG8_SB(b, h) + boff + n * 2048 + k * 1024); } while (0)
; #define PG8_WAIT_V(n) asm volatile("s_waitcnt vmcnt(" #n ")" ::: "memory")
; #define PG8_WAIT_L(n) asm volatile("s_waitcnt lgkmcnt(" #n ")" ::: "memory")
; #define PG8_WAIT_V_SEL(sel) asm volatile("s_cmp_eq_u32 %0, 0\n\ts_cbranch_scc1 .Lw8_%=\n\ts_waitcnt vmcnt(22)\n\ts_branch .Lwd_%=\n.Lw8_%=:\n\ts_waitcnt vmcnt(8)\n.Lwd_%=:" :: "s"(sel) : "memory", "scc")
; #define PG8_BAR __builtin_amdgcn_s_barrier()
; #define PG8_SCHED __builtin_amdgcn_sched_barrier(0)
;     ...
;             PG8_WAIT_L(0); PG8_BAR; PG8_MMA(0, 0, At, B0); PG8_MMA(0, 1, At, B1); PG8_BAR; PG8_SCHED;
;             PG8_LDA(At, 0, 1); PG8_STAGE(PG8_SB(0, 0), b2, voffB); PG8_STAGE(PG8_SB(0, 1), b2 + hstep, voffB); PG8_STAGE(PG8_SA(0, 0), a2, voffA);
;             PG8_WAIT_V_SEL(relax);
;             PG8_WAIT_L(0); PG8_BAR; PG8_MMA(1, 0, At, B0); PG8_MMA(1, 1, At, B1); PG8_BAR; PG8_SCHED;
;             PG8_LDB(B0, 1, 0); PG8_LDB(B1, 1, 1); PG8_SCHED; PG8_LDA(At, 1, 0); PG8_STAGE(PG8_SA(0, 1), a2 + hstep, voffA);
;             PG8_WAIT_V(8); PG8_WAIT_L(0); PG8_BAR; PG8_MMA(0, 0, At, B0); PG8_MMA(0, 1, At, B1); PG8_BAR; PG8_SCHED;
;             PG8_LDA(At, 1, 1); PG8_STAGE(PG8_SB(1, 0), b3, voffB); PG8_STAGE(PG8_SB(1, 1), b3 + hstep, voffB); PG8_STAGE(PG8_SA(1, 0), a3, voffA);
.Lrlx_f1_1_b:
	s_waitcnt lgkmcnt(0)
	s_setprio 1
	s_barrier
	v_mfma_f32_16x16x32_bf16 v[30:33], v[66:69], v[162:165], v[30:33]
	v_mfma_f32_16x16x32_bf16 v[30:33], v[70:73], v[166:169], v[30:33]
	v_mfma_f32_16x16x32_bf16 v[26:29], v[66:69], v[170:173], v[26:29]
	v_mfma_f32_16x16x32_bf16 v[26:29], v[70:73], v[174:177], v[26:29]
	v_mfma_f32_16x16x32_bf16 v[62:65], v[66:69], v[178:181], v[62:65]
	v_mfma_f32_16x16x32_bf16 v[62:65], v[70:73], v[184:187], v[62:65]
	v_mfma_f32_16x16x32_bf16 v[58:61], v[66:69], v[220:223], v[58:61]
	v_mfma_f32_16x16x32_bf16 v[58:61], v[70:73], v[224:227], v[58:61]
	v_mfma_f32_16x16x32_bf16 v[50:53], v[82:85], v[220:223], v[50:53]
	v_mfma_f32_16x16x32_bf16 v[50:53], v[142:145], v[224:227], v[50:53]
	v_mfma_f32_16x16x32_bf16 v[54:57], v[82:85], v[178:181], v[54:57]
	v_mfma_f32_16x16x32_bf16 v[54:57], v[142:145], v[184:187], v[54:57]
	v_mfma_f32_16x16x32_bf16 v[18:21], v[82:85], v[170:173], v[18:21]
	v_mfma_f32_16x16x32_bf16 v[18:21], v[142:145], v[174:177], v[18:21]
	v_mfma_f32_16x16x32_bf16 v[22:25], v[82:85], v[162:165], v[22:25]
	v_mfma_f32_16x16x32_bf16 v[22:25], v[142:145], v[166:169], v[22:25]
	v_mfma_f32_16x16x32_bf16 v[14:17], v[146:149], v[162:165], v[14:17]
	v_mfma_f32_16x16x32_bf16 v[14:17], v[150:153], v[166:169], v[14:17]
	v_mfma_f32_16x16x32_bf16 v[10:13], v[146:149], v[170:173], v[10:13]
	v_mfma_f32_16x16x32_bf16 v[10:13], v[150:153], v[174:177], v[10:13]
	v_mfma_f32_16x16x32_bf16 v[46:49], v[146:149], v[178:181], v[46:49]
	v_mfma_f32_16x16x32_bf16 v[46:49], v[150:153], v[184:187], v[46:49]
	v_mfma_f32_16x16x32_bf16 v[38:41], v[146:149], v[220:223], v[38:41]
	v_mfma_f32_16x16x32_bf16 v[38:41], v[150:153], v[224:227], v[38:41]
	v_mfma_f32_16x16x32_bf16 v[42:45], v[154:157], v[220:223], v[42:45]
	v_mfma_f32_16x16x32_bf16 v[42:45], v[158:161], v[224:227], v[42:45]
	v_mfma_f32_16x16x32_bf16 v[34:37], v[154:157], v[178:181], v[34:37]
	v_mfma_f32_16x16x32_bf16 v[34:37], v[158:161], v[184:187], v[34:37]
	v_mfma_f32_16x16x32_bf16 v[2:5], v[154:157], v[170:173], v[2:5]
	v_mfma_f32_16x16x32_bf16 v[2:5], v[158:161], v[174:177], v[2:5]
	v_mfma_f32_16x16x32_bf16 v[6:9], v[154:157], v[162:165], v[6:9]
	v_mfma_f32_16x16x32_bf16 v[6:9], v[158:161], v[166:169], v[6:9]
	s_barrier
	s_setprio 0
	s_add_i32 s19, 0, 0x18000
	s_add_i32 s51, 0, 0x1c000
	ds_read_b128 v[66:69], v200 offset:32768
	ds_read_b128 v[70:73], v200 offset:33792
	ds_read_b128 v[82:85], v200 offset:34816
	ds_read_b128 v[142:145], v200 offset:35840
	ds_read_b128 v[146:149], v200 offset:49152
	ds_read_b128 v[150:153], v200 offset:50176
	ds_read_b128 v[154:157], v200 offset:51200
	ds_read_b128 v[158:161], v200 offset:52224
	s_add_u32 s12, s40, 0x80000
	s_addc_u32 s13, s41, 0
	s_mov_b32 m0, s44
	ds_read_b128 v[162:165], v219 offset:32768
	ds_read_b128 v[166:169], v219 offset:33792
	ds_read_b128 v[170:173], v219 offset:34816
	ds_read_b128 v[174:177], v219 offset:35840
	ds_read_b128 v[178:181], v219 offset:36864
	ds_read_b128 v[184:187], v219 offset:37888
	ds_read_b128 v[220:223], v219 offset:38912
	ds_read_b128 v[224:227], v219 offset:39936
	global_load_lds_dwordx4 v188, s[12:13]
	s_mov_b32 m0, s46
	s_nop 0
	global_load_lds_dwordx4 v190, s[12:13]
	s_waitcnt vmcnt(8)
	s_waitcnt lgkmcnt(0)
	s_setprio 1
	s_barrier
	v_mfma_f32_16x16x32_bf16 v[114:117], v[66:69], v[162:165], v[114:117]
	v_mfma_f32_16x16x32_bf16 v[114:117], v[70:73], v[166:169], v[114:117]
	v_mfma_f32_16x16x32_bf16 v[110:113], v[66:69], v[170:173], v[110:113]
	v_mfma_f32_16x16x32_bf16 v[110:113], v[70:73], v[174:177], v[110:113]
	v_mfma_f32_16x16x32_bf16 v[78:81], v[66:69], v[178:181], v[78:81]
	v_mfma_f32_16x16x32_bf16 v[78:81], v[70:73], v[184:187], v[78:81]
	v_mfma_f32_16x16x32_bf16 v[74:77], v[66:69], v[220:223], v[74:77]
	v_mfma_f32_16x16x32_bf16 v[74:77], v[70:73], v[224:227], v[74:77]
	v_mfma_f32_16x16x32_bf16 v[134:137], v[82:85], v[220:223], v[134:137]
	v_mfma_f32_16x16x32_bf16 v[134:137], v[142:145], v[224:227], v[134:137]
	v_mfma_f32_16x16x32_bf16 v[138:141], v[82:85], v[178:181], v[138:141]
	v_mfma_f32_16x16x32_bf16 v[138:141], v[142:145], v[184:187], v[138:141]
	v_mfma_f32_16x16x32_bf16 v[102:105], v[82:85], v[170:173], v[102:105]
	v_mfma_f32_16x16x32_bf16 v[102:105], v[142:145], v[174:177], v[102:105]
	v_mfma_f32_16x16x32_bf16 v[106:109], v[82:85], v[162:165], v[106:109]
	v_mfma_f32_16x16x32_bf16 v[106:109], v[142:145], v[166:169], v[106:109]
	v_mfma_f32_16x16x32_bf16 v[98:101], v[146:149], v[162:165], v[98:101]
	v_mfma_f32_16x16x32_bf16 v[98:101], v[150:153], v[166:169], v[98:101]
	v_mfma_f32_16x16x32_bf16 v[94:97], v[146:149], v[170:173], v[94:97]
	v_mfma_f32_16x16x32_bf16 v[94:97], v[150:153], v[174:177], v[94:97]
	v_mfma_f32_16x16x32_bf16 v[130:133], v[146:149], v[178:181], v[130:133]
	v_mfma_f32_16x16x32_bf16 v[130:133], v[150:153], v[184:187], v[130:133]
	v_mfma_f32_16x16x32_bf16 v[126:129], v[146:149], v[220:223], v[126:129]
	v_mfma_f32_16x16x32_bf16 v[126:129], v[150:153], v[224:227], v[126:129]
	v_mfma_f32_16x16x32_bf16 v[118:121], v[154:157], v[220:223], v[118:121]
	v_mfma_f32_16x16x32_bf16 v[118:121], v[158:161], v[224:227], v[118:121]
	v_mfma_f32_16x16x32_bf16 v[122:125], v[154:157], v[178:181], v[122:125]
	v_mfma_f32_16x16x32_bf16 v[122:125], v[158:161], v[184:187], v[122:125]
	v_mfma_f32_16x16x32_bf16 v[86:89], v[154:157], v[170:173], v[86:89]
	v_mfma_f32_16x16x32_bf16 v[86:89], v[158:161], v[174:177], v[86:89]
	v_mfma_f32_16x16x32_bf16 v[90:93], v[154:157], v[162:165], v[90:93]
	v_mfma_f32_16x16x32_bf16 v[90:93], v[158:161], v[166:169], v[90:93]
	s_barrier
; #define PG8_STAGE(bufoff, gbase, voff) do { _Pragma("unroll") for (int _i = 0; _i < 2; ++_i) \
;         __builtin_amdgcn_global_load_lds((const unsigned*)((const char*)(gbase) + (voff)[_i]), (PG8_LAS unsigned*)(lds + (bufoff) + ldsw + _i * 8192), 16, 0, 0); } while (0)
; #define PG8_LDA(dst, b, h) do { _Pragma("unroll") for (int m = 0; m < 4; ++m) _Pragma("unroll") for (int k = 0; k < 2; ++k) dst[m][k] = *(const PG8_LAS bf16x8*)(lds + PG8_SA(b, h) + aoff + m * 2048 + k * 1024); } while (0)
; #define PG8_LDB(dst, b, h) do { _Pragma("unroll") for (int n = 0; n < 2; ++n) _Pragma("unroll") for (int k = 0; k < 2; ++k) dst[n][k] = *(const PG8_LAS bf16x8*)(lds + PG8_SB(b, h) + boff + n * 2048 + k * 1024); } while (0)
; #define PG8_WAIT_V(n) asm volatile("s_waitcnt vmcnt(" #n ")" ::: "memory")
; #define PG8_WAIT_L(n) asm volatile("s_waitcnt lgkmcnt(" #n ")" ::: "memory")
; #define PG8_BAR __builtin_amdgcn_s_barrier()
; #define PG8_SCHED __builtin_amdgcn_sched_barrier(0)
;     ...
;             PG8_LDB(B0, 1, 0); PG8_LDB(B1, 1, 1); PG8_SCHED; PG8_LDA(At, 1, 0); PG8_STAGE(PG8_SA(0, 1), a2 + hstep, voffA);
;             PG8_WAIT_V(8); PG8_WAIT_L(0); PG8_BAR; PG8_MMA(0, 0, At, B0); PG8_MMA(0, 1, At, B1); PG8_BAR; PG8_SCHED;
;             PG8_LDA(At, 1, 1); PG8_STAGE(PG8_SB(1, 0), b3, voffB); PG8_STAGE(PG8_SB(1, 1), b3 + hstep, voffB); PG8_STAGE(PG8_SA(1, 0), a3, voffA);
;             PG8_WAIT_V(8); PG8_WAIT_L(0); PG8_BAR; PG8_MMA(1, 0, At, B0); PG8_MMA(1, 1, At, B1); PG8_BAR; PG8_SCHED;
	s_setprio 0
	s_add_i32 s12, s19, s37
	s_mov_b32 m0, s12
	ds_read_b128 v[162:165], v219 offset:49152
	ds_read_b128 v[166:169], v219 offset:50176
	ds_read_b128 v[170:173], v219 offset:51200
	ds_read_b128 v[174:177], v219 offset:52224
	ds_read_b128 v[178:181], v219 offset:53248
	ds_read_b128 v[184:187], v219 offset:54272
	ds_read_b128 v[220:223], v219 offset:55296
	ds_read_b128 v[224:227], v219 offset:56320
	s_add_u32 s100, vcc_lo, 0x80
	s_addc_u32 s101, vcc_hi, 0
	global_load_lds_dwordx4 v182, s[100:101]
	s_add_i32 m0, s12, 0x2000
	s_add_u32 s12, vcc_lo, 0x80080
	s_addc_u32 s13, vcc_hi, 0
	s_add_i32 s19, s51, s37
	global_load_lds_dwordx4 v192, s[100:101]
	s_mov_b32 m0, s19
	s_nop 0
	global_load_lds_dwordx4 v182, s[12:13]
	s_add_i32 m0, s19, 0x2000
	s_nop 0
	global_load_lds_dwordx4 v192, s[12:13]
	s_mov_b32 m0, s45
	s_nop 0
	s_add_u32 s100, s40, 0x80
	s_addc_u32 s101, s41, 0
	global_load_lds_dwordx4 v188, s[100:101]
	s_mov_b32 m0, s24
	s_nop 0
	global_load_lds_dwordx4 v190, s[100:101]
	s_waitcnt vmcnt(8)
	s_waitcnt lgkmcnt(0)
	s_setprio 1
	s_barrier
	v_mfma_f32_16x16x32_bf16 v[30:33], v[66:69], v[162:165], v[30:33]
	v_mfma_f32_16x16x32_bf16 v[30:33], v[70:73], v[166:169], v[30:33]
	v_mfma_f32_16x16x32_bf16 v[26:29], v[66:69], v[170:173], v[26:29]
	v_mfma_f32_16x16x32_bf16 v[26:29], v[70:73], v[174:177], v[26:29]
	v_mfma_f32_16x16x32_bf16 v[62:65], v[66:69], v[178:181], v[62:65]
	v_mfma_f32_16x16x32_bf16 v[62:65], v[70:73], v[184:187], v[62:65]
	v_mfma_f32_16x16x32_bf16 v[58:61], v[66:69], v[220:223], v[58:61]
	v_mfma_f32_16x16x32_bf16 v[58:61], v[70:73], v[224:227], v[58:61]
	v_mfma_f32_16x16x32_bf16 v[50:53], v[82:85], v[220:223], v[50:53]
	v_mfma_f32_16x16x32_bf16 v[50:53], v[142:145], v[224:227], v[50:53]
	v_mfma_f32_16x16x32_bf16 v[54:57], v[82:85], v[178:181], v[54:57]
	v_mfma_f32_16x16x32_bf16 v[54:57], v[142:145], v[184:187], v[54:57]
	v_mfma_f32_16x16x32_bf16 v[18:21], v[82:85], v[170:173], v[18:21]
	v_mfma_f32_16x16x32_bf16 v[18:21], v[142:145], v[174:177], v[18:21]
	v_mfma_f32_16x16x32_bf16 v[22:25], v[82:85], v[162:165], v[22:25]
	v_mfma_f32_16x16x32_bf16 v[22:25], v[142:145], v[166:169], v[22:25]
	v_mfma_f32_16x16x32_bf16 v[14:17], v[146:149], v[162:165], v[14:17]
	v_mfma_f32_16x16x32_bf16 v[14:17], v[150:153], v[166:169], v[14:17]
	v_mfma_f32_16x16x32_bf16 v[10:13], v[146:149], v[170:173], v[10:13]
	v_mfma_f32_16x16x32_bf16 v[10:13], v[150:153], v[174:177], v[10:13]
	v_mfma_f32_16x16x32_bf16 v[46:49], v[146:149], v[178:181], v[46:49]
	v_mfma_f32_16x16x32_bf16 v[46:49], v[150:153], v[184:187], v[46:49]
	v_mfma_f32_16x16x32_bf16 v[38:41], v[146:149], v[220:223], v[38:41]
	v_mfma_f32_16x16x32_bf16 v[38:41], v[150:153], v[224:227], v[38:41]
	v_mfma_f32_16x16x32_bf16 v[42:45], v[154:157], v[220:223], v[42:45]
	v_mfma_f32_16x16x32_bf16 v[42:45], v[158:161], v[224:227], v[42:45]
	v_mfma_f32_16x16x32_bf16 v[34:37], v[154:157], v[178:181], v[34:37]
	v_mfma_f32_16x16x32_bf16 v[34:37], v[158:161], v[184:187], v[34:37]
	v_mfma_f32_16x16x32_bf16 v[2:5], v[154:157], v[170:173], v[2:5]
	v_mfma_f32_16x16x32_bf16 v[2:5], v[158:161], v[174:177], v[2:5]
	v_mfma_f32_16x16x32_bf16 v[6:9], v[154:157], v[162:165], v[6:9]
	v_mfma_f32_16x16x32_bf16 v[6:9], v[158:161], v[166:169], v[6:9]
	s_barrier
	s_setprio 0
	s_add_i32 s0, s0, 2
	s_add_u32 s66, s66, 0x100
	s_addc_u32 s67, s67, 0
	s_cmp_gt_u32 s0, 29
	s_mov_b64 s[12:13], s[96:97]
	s_mov_b32 s101, 0
	s_cbranch_scc0 .LBB0_1327
	s_branch .Lrlx_f1_x
.Lrlx_f1_0:
	s_waitcnt vmcnt(22)
	s_branch .Lrlx_f1_0_b

; #define PG8_BAR __builtin_amdgcn_s_barrier()
;     ...
;         }
;         unsigned long long tp0 = 0; if constexpr (TP == 1) tp0 = __builtin_amdgcn_s_memrealtime();
;         if constexpr (ALIGN_EPI) { if (wr == 0) PG8_BAR; }
.Lrlx_f1_x:
	s_and_b64 vcc, exec, s[78:79]
	s_cbranch_vccz .LBB0_1330
	s_barrier
